# weight-conversion tile: all 16 weight and gain loads issued up front with a single wait instead of a load-wait per element
# speedup vs baseline: 1.0397x; 1.0056x over previous
; DI void wconv_tile(const float* __restrict__ src, int K, int Ns, const float* __restrict__ g, bf16_t* __restrict__ dst, int mode, int nt, int kt, char* lds) {
;     ...
;     const int nl = tid & 63, n = nt * 64 + nl;
;     int sc;
;     if (mode == 0) sc = n;
;     else if (mode == 1) sc = n < 640 ? n : n < 2432 ? n + 32 : n < 2464 ? n - 2432 + 640 : -1;
;     else sc = (n & 127) < 96 ? (n >> 7) * 96 + (n & 127) : -1;
; #pragma unroll
;     for (int i = 0; i < 16; ++i) {
;       const int kl = (tid >> 6) + 4 * i, k = kt * 64 + kl;
;       float v = 0.f;
;       if (sc >= 0) { v = __builtin_nontemporal_load(src + (size_t)k * Ns + sc); if (g) v *= g[k]; }
.LBB0_373:
	s_or_b64 exec, exec, s[0:1]
	v_mul_lo_u32 v11, v16, v11
	v_sub_u32_e32 v10, v10, v11
	v_bfe_u32 v12, v19, 6, 2
	v_cmp_lt_i32_e64 s[0:1], -1, v0
	v_lshlrev_b32_e32 v10, 6, v10
	v_lshl_add_u64 v[14:15], v[0:1], 2, v[14:15]
	v_cmp_ne_u64_e32 vcc, 0, v[8:9]
	v_mov_b32_e32 v21, 0
	v_mov_b32_e32 v0, 0
	s_and_saveexec_b64 s[42:43], s[0:1]
	s_cbranch_execz .Lwc_skip
	v_ashrrev_i32_e32 v135, 31, v10
	v_mul_lo_u32 v135, v4, v135
	v_or_b32_e32 v134, v12, v10
	v_mul_lo_u32 v138, v5, v134
	v_mad_u64_u32 v[132:133], s[2:3], v4, v134, 0
	v_add3_u32 v133, v133, v135, v138
	v_lshl_add_u64 v[132:133], v[132:133], 2, v[14:15]
	global_load_dword v100, v[132:133], off nt
	v_or3_b32 v134, v12, v10, 4
	v_mul_lo_u32 v138, v5, v134
	v_mad_u64_u32 v[132:133], s[2:3], v4, v134, 0
	v_add3_u32 v133, v133, v135, v138
	v_lshl_add_u64 v[132:133], v[132:133], 2, v[14:15]
	global_load_dword v101, v[132:133], off nt
	v_or3_b32 v134, v12, v10, 8
	v_mul_lo_u32 v138, v5, v134
	v_mad_u64_u32 v[132:133], s[2:3], v4, v134, 0
	v_add3_u32 v133, v133, v135, v138
	v_lshl_add_u64 v[132:133], v[132:133], 2, v[14:15]
	global_load_dword v102, v[132:133], off nt
	v_or3_b32 v134, v12, v10, 12
	v_mul_lo_u32 v138, v5, v134
	v_mad_u64_u32 v[132:133], s[2:3], v4, v134, 0
	v_add3_u32 v133, v133, v135, v138
	v_lshl_add_u64 v[132:133], v[132:133], 2, v[14:15]
	global_load_dword v103, v[132:133], off nt
	v_or3_b32 v134, v12, v10, 16
	v_mul_lo_u32 v138, v5, v134
	v_mad_u64_u32 v[132:133], s[2:3], v4, v134, 0
	v_add3_u32 v133, v133, v135, v138
	v_lshl_add_u64 v[132:133], v[132:133], 2, v[14:15]
	global_load_dword v104, v[132:133], off nt
	v_or3_b32 v134, v12, v10, 20
	v_mul_lo_u32 v138, v5, v134
	v_mad_u64_u32 v[132:133], s[2:3], v4, v134, 0
	v_add3_u32 v133, v133, v135, v138
	v_lshl_add_u64 v[132:133], v[132:133], 2, v[14:15]
	global_load_dword v105, v[132:133], off nt
	v_or3_b32 v134, v12, v10, 24
	v_mul_lo_u32 v138, v5, v134
	v_mad_u64_u32 v[132:133], s[2:3], v4, v134, 0
	v_add3_u32 v133, v133, v135, v138
	v_lshl_add_u64 v[132:133], v[132:133], 2, v[14:15]
	global_load_dword v106, v[132:133], off nt
	v_or3_b32 v134, v12, v10, 28
	v_mul_lo_u32 v138, v5, v134
	v_mad_u64_u32 v[132:133], s[2:3], v4, v134, 0
	v_add3_u32 v133, v133, v135, v138
	v_lshl_add_u64 v[132:133], v[132:133], 2, v[14:15]
	global_load_dword v107, v[132:133], off nt
	v_or3_b32 v134, v12, v10, 32
	v_mul_lo_u32 v138, v5, v134
	v_mad_u64_u32 v[132:133], s[2:3], v4, v134, 0
	v_add3_u32 v133, v133, v135, v138
	v_lshl_add_u64 v[132:133], v[132:133], 2, v[14:15]
	global_load_dword v108, v[132:133], off nt
	v_or3_b32 v134, v12, v10, 36
	v_mul_lo_u32 v138, v5, v134
	v_mad_u64_u32 v[132:133], s[2:3], v4, v134, 0
	v_add3_u32 v133, v133, v135, v138
	v_lshl_add_u64 v[132:133], v[132:133], 2, v[14:15]
	global_load_dword v109, v[132:133], off nt
	v_or3_b32 v134, v12, v10, 40
	v_mul_lo_u32 v138, v5, v134
	v_mad_u64_u32 v[132:133], s[2:3], v4, v134, 0
	v_add3_u32 v133, v133, v135, v138
	v_lshl_add_u64 v[132:133], v[132:133], 2, v[14:15]
	global_load_dword v110, v[132:133], off nt
	v_or3_b32 v134, v12, v10, 44
	v_mul_lo_u32 v138, v5, v134
	v_mad_u64_u32 v[132:133], s[2:3], v4, v134, 0
	v_add3_u32 v133, v133, v135, v138
	v_lshl_add_u64 v[132:133], v[132:133], 2, v[14:15]
	global_load_dword v111, v[132:133], off nt
	v_or3_b32 v134, v12, v10, 48
	v_mul_lo_u32 v138, v5, v134
	v_mad_u64_u32 v[132:133], s[2:3], v4, v134, 0
	v_add3_u32 v133, v133, v135, v138
	v_lshl_add_u64 v[132:133], v[132:133], 2, v[14:15]
	global_load_dword v112, v[132:133], off nt
	v_or3_b32 v134, v12, v10, 52
	v_mul_lo_u32 v138, v5, v134
	v_mad_u64_u32 v[132:133], s[2:3], v4, v134, 0
	v_add3_u32 v133, v133, v135, v138
	v_lshl_add_u64 v[132:133], v[132:133], 2, v[14:15]
	global_load_dword v113, v[132:133], off nt
	v_or3_b32 v134, v12, v10, 56
	v_mul_lo_u32 v138, v5, v134
	v_mad_u64_u32 v[132:133], s[2:3], v4, v134, 0
	v_add3_u32 v133, v133, v135, v138
	v_lshl_add_u64 v[132:133], v[132:133], 2, v[14:15]
	global_load_dword v114, v[132:133], off nt
	v_or3_b32 v134, v12, v10, 60
	v_mul_lo_u32 v138, v5, v134
	v_mad_u64_u32 v[132:133], s[2:3], v4, v134, 0
	v_add3_u32 v133, v133, v135, v138
	v_lshl_add_u64 v[132:133], v[132:133], 2, v[14:15]
	global_load_dword v115, v[132:133], off nt
	s_and_saveexec_b64 s[52:53], vcc
	s_cbranch_execz .Lwc_nog
	v_or_b32_e32 v134, v12, v10
	v_ashrrev_i32_e32 v135, 31, v134
	v_lshl_add_u64 v[136:137], v[134:135], 2, v[8:9]
	global_load_dword v116, v[136:137], off
	global_load_dword v117, v[136:137], off offset:16
	global_load_dword v118, v[136:137], off offset:32
	global_load_dword v119, v[136:137], off offset:48
	global_load_dword v120, v[136:137], off offset:64
	global_load_dword v121, v[136:137], off offset:80
	global_load_dword v122, v[136:137], off offset:96
	global_load_dword v123, v[136:137], off offset:112
	global_load_dword v124, v[136:137], off offset:128
	global_load_dword v125, v[136:137], off offset:144
	global_load_dword v126, v[136:137], off offset:160
	global_load_dword v127, v[136:137], off offset:176
	global_load_dword v128, v[136:137], off offset:192
	global_load_dword v129, v[136:137], off offset:208
	global_load_dword v130, v[136:137], off offset:224
	global_load_dword v131, v[136:137], off offset:240

; DI void wconv_tile(const float* __restrict__ src, int K, int Ns, const float* __restrict__ g, bf16_t* __restrict__ dst, int mode, int nt, int kt, char* lds) {
;     ...
;     for (int i = 0; i < 16; ++i) {
;       const int kl = (tid >> 6) + 4 * i, k = kt * 64 + kl;
;       float v = 0.f;
;       if (sc >= 0) { v = __builtin_nontemporal_load(src + (size_t)k * Ns + sc); if (g) v *= g[k]; }
;       tl[kl * 65 + nl] = v;
.Lwc_skip:
	s_or_b64 exec, exec, s[42:43]
	s_and_saveexec_b64 s[42:43], s[0:1]
	s_cbranch_execz .LBB0_377
	v_or_b32_e32 v16, v12, v10
	v_ashrrev_i32_e32 v17, 31, v16
	v_mul_lo_u32 v0, v4, v17
	v_mul_lo_u32 v11, v5, v16
	v_mad_u64_u32 v[22:23], s[2:3], v4, v16, 0
	v_add3_u32 v23, v23, v0, v11
	v_lshl_add_u64 v[22:23], v[22:23], 2, v[14:15]
	s_waitcnt vmcnt(0)
	v_mov_b32_e32 v0, v100
	s_and_saveexec_b64 s[52:53], vcc
	s_cbranch_execz .LBB0_376
	v_lshl_add_u64 v[16:17], v[16:17], 2, v[8:9]
	v_mov_b32_e32 v11, v116
	s_waitcnt vmcnt(0)
	v_mul_f32_e32 v0, v0, v11

; DI void wconv_tile(const float* __restrict__ src, int K, int Ns, const float* __restrict__ g, bf16_t* __restrict__ dst, int mode, int nt, int kt, char* lds) {
;     ...
;     for (int i = 0; i < 16; ++i) {
;       const int kl = (tid >> 6) + 4 * i, k = kt * 64 + kl;
;       float v = 0.f;
;       if (sc >= 0) { v = __builtin_nontemporal_load(src + (size_t)k * Ns + sc); if (g) v *= g[k]; }
;       tl[kl * 65 + nl] = v;
.LBB0_377:
	s_or_b64 exec, exec, s[42:43]
	v_mul_u32_u24_e32 v17, 0x104, v12
	v_lshlrev_b32_e32 v16, 2, v13
	v_add3_u32 v11, v250, v17, v16
	s_waitcnt vmcnt(0)
	ds_write_b32 v11, v0
	v_ashrrev_i32_e32 v11, 31, v10
	v_mul_lo_u32 v0, v4, v11
	s_and_saveexec_b64 s[42:43], s[0:1]
	s_cbranch_execz .LBB0_381
	v_or3_b32 v13, v12, v10, 4
	v_mul_lo_u32 v21, v5, v13
	v_mad_u64_u32 v[22:23], s[2:3], v4, v13, 0
	v_add3_u32 v23, v23, v0, v21
	v_lshl_add_u64 v[22:23], v[22:23], 2, v[14:15]
	s_waitcnt vmcnt(0)
	v_mov_b32_e32 v21, v101
	s_and_saveexec_b64 s[52:53], vcc
	s_cbranch_execz .LBB0_380
	v_mov_b32_e32 v13, v1
	v_lshl_add_u64 v[22:23], v[12:13], 0, v[10:11]
	v_lshl_add_u64 v[22:23], v[22:23], 2, v[8:9]
	v_mov_b32_e32 v13, v117
	s_waitcnt vmcnt(0)
	v_mul_f32_e32 v21, v21, v13

; DI void wconv_tile(const float* __restrict__ src, int K, int Ns, const float* __restrict__ g, bf16_t* __restrict__ dst, int mode, int nt, int kt, char* lds) {
;     ...
;     for (int i = 0; i < 16; ++i) {
;       const int kl = (tid >> 6) + 4 * i, k = kt * 64 + kl;
;       float v = 0.f;
;       if (sc >= 0) { v = __builtin_nontemporal_load(src + (size_t)k * Ns + sc); if (g) v *= g[k]; }
;       tl[kl * 65 + nl] = v;
.LBB0_381:
	s_or_b64 exec, exec, s[42:43]
	v_add_u32_e32 v22, 0x410, v17
	v_add3_u32 v13, v250, v22, v16
	v_mov_b32_e32 v17, 0
	v_mov_b32_e32 v23, 0
	s_waitcnt vmcnt(0)
	ds_write_b32 v13, v21
	s_and_saveexec_b64 s[42:43], s[0:1]
	s_cbranch_execz .LBB0_385
	v_or3_b32 v13, v12, v10, 8
	v_mul_lo_u32 v21, v5, v13
	v_mad_u64_u32 v[24:25], s[2:3], v4, v13, 0
	v_add3_u32 v25, v25, v0, v21
	v_lshl_add_u64 v[24:25], v[24:25], 2, v[14:15]
	s_waitcnt vmcnt(0)
	v_mov_b32_e32 v23, v102
	s_and_saveexec_b64 s[52:53], vcc
	s_cbranch_execz .LBB0_384
	v_mov_b32_e32 v13, v1
	v_lshl_add_u64 v[24:25], v[12:13], 0, v[10:11]
	v_lshl_add_u64 v[24:25], v[24:25], 2, v[8:9]
	v_mov_b32_e32 v13, v118
	s_waitcnt vmcnt(0)
	v_mul_f32_e32 v23, v23, v13

; DI void wconv_tile(const float* __restrict__ src, int K, int Ns, const float* __restrict__ g, bf16_t* __restrict__ dst, int mode, int nt, int kt, char* lds) {
;     ...
;     for (int i = 0; i < 16; ++i) {
;       const int kl = (tid >> 6) + 4 * i, k = kt * 64 + kl;
;       float v = 0.f;
;       if (sc >= 0) { v = __builtin_nontemporal_load(src + (size_t)k * Ns + sc); if (g) v *= g[k]; }
;       tl[kl * 65 + nl] = v;
.LBB0_385:
	s_or_b64 exec, exec, s[42:43]
	v_add_u32_e32 v21, 0x410, v22
	v_add3_u32 v13, v250, v21, v16
	s_waitcnt vmcnt(0)
	ds_write_b32 v13, v23
	s_and_saveexec_b64 s[42:43], s[0:1]
	s_cbranch_execz .LBB0_389
	v_or3_b32 v13, v12, v10, 12
	v_mul_lo_u32 v17, v5, v13
	v_mad_u64_u32 v[22:23], s[2:3], v4, v13, 0
	v_add3_u32 v23, v23, v0, v17
	v_lshl_add_u64 v[22:23], v[22:23], 2, v[14:15]
	s_waitcnt vmcnt(0)
	v_mov_b32_e32 v17, v103
	s_and_saveexec_b64 s[52:53], vcc
	s_cbranch_execz .LBB0_388
	v_mov_b32_e32 v13, v1
	v_lshl_add_u64 v[22:23], v[12:13], 0, v[10:11]
	v_lshl_add_u64 v[22:23], v[22:23], 2, v[8:9]
	v_mov_b32_e32 v13, v119
	s_waitcnt vmcnt(0)
	v_mul_f32_e32 v17, v17, v13

; DI void wconv_tile(const float* __restrict__ src, int K, int Ns, const float* __restrict__ g, bf16_t* __restrict__ dst, int mode, int nt, int kt, char* lds) {
;     ...
;     for (int i = 0; i < 16; ++i) {
;       const int kl = (tid >> 6) + 4 * i, k = kt * 64 + kl;
;       float v = 0.f;
;       if (sc >= 0) { v = __builtin_nontemporal_load(src + (size_t)k * Ns + sc); if (g) v *= g[k]; }
;       tl[kl * 65 + nl] = v;
.LBB0_389:
	s_or_b64 exec, exec, s[42:43]
	v_add_u32_e32 v21, 0x410, v21
	v_add3_u32 v13, v250, v21, v16
	s_waitcnt vmcnt(0)
	ds_write_b32 v13, v17
	v_mov_b32_e32 v17, 0
	v_mov_b32_e32 v22, 0
	s_and_saveexec_b64 s[42:43], s[0:1]
	s_cbranch_execz .LBB0_393
	v_or3_b32 v13, v12, v10, 16
	v_mul_lo_u32 v24, v5, v13
	v_mad_u64_u32 v[22:23], s[2:3], v4, v13, 0
	v_add3_u32 v23, v23, v0, v24
	v_lshl_add_u64 v[22:23], v[22:23], 2, v[14:15]
	s_waitcnt vmcnt(0)
	v_mov_b32_e32 v22, v104
	s_and_saveexec_b64 s[52:53], vcc
	s_cbranch_execz .LBB0_392
	v_mov_b32_e32 v13, v1
	v_lshl_add_u64 v[24:25], v[12:13], 0, v[10:11]
	v_lshl_add_u64 v[24:25], v[24:25], 2, v[8:9]
	v_mov_b32_e32 v13, v120
	s_waitcnt vmcnt(0)
	v_mul_f32_e32 v22, v22, v13

; DI void wconv_tile(const float* __restrict__ src, int K, int Ns, const float* __restrict__ g, bf16_t* __restrict__ dst, int mode, int nt, int kt, char* lds) {
;     ...
;     for (int i = 0; i < 16; ++i) {
;       const int kl = (tid >> 6) + 4 * i, k = kt * 64 + kl;
;       float v = 0.f;
;       if (sc >= 0) { v = __builtin_nontemporal_load(src + (size_t)k * Ns + sc); if (g) v *= g[k]; }
;       tl[kl * 65 + nl] = v;
.LBB0_393:
	s_or_b64 exec, exec, s[42:43]
	v_add_u32_e32 v21, 0x410, v21
	v_add3_u32 v13, v250, v21, v16
	s_waitcnt vmcnt(0)
	ds_write_b32 v13, v22
	s_and_saveexec_b64 s[42:43], s[0:1]
	s_cbranch_execz .LBB0_397
	v_or3_b32 v13, v12, v10, 20
	v_mul_lo_u32 v17, v5, v13
	v_mad_u64_u32 v[22:23], s[2:3], v4, v13, 0
	v_add3_u32 v23, v23, v0, v17
	v_lshl_add_u64 v[22:23], v[22:23], 2, v[14:15]
	s_waitcnt vmcnt(0)
	v_mov_b32_e32 v17, v105
	s_and_saveexec_b64 s[52:53], vcc
	s_cbranch_execz .LBB0_396
	v_mov_b32_e32 v13, v1
	v_lshl_add_u64 v[22:23], v[12:13], 0, v[10:11]
	v_lshl_add_u64 v[22:23], v[22:23], 2, v[8:9]
	v_mov_b32_e32 v13, v121
	s_waitcnt vmcnt(0)
	v_mul_f32_e32 v17, v17, v13

; DI void wconv_tile(const float* __restrict__ src, int K, int Ns, const float* __restrict__ g, bf16_t* __restrict__ dst, int mode, int nt, int kt, char* lds) {
;     ...
;     for (int i = 0; i < 16; ++i) {
;       const int kl = (tid >> 6) + 4 * i, k = kt * 64 + kl;
;       float v = 0.f;
;       if (sc >= 0) { v = __builtin_nontemporal_load(src + (size_t)k * Ns + sc); if (g) v *= g[k]; }
;       tl[kl * 65 + nl] = v;
.LBB0_397:
	s_or_b64 exec, exec, s[42:43]
	v_add_u32_e32 v21, 0x410, v21
	v_add3_u32 v13, v250, v21, v16
	s_waitcnt vmcnt(0)
	ds_write_b32 v13, v17
	v_mov_b32_e32 v17, 0
	v_mov_b32_e32 v22, 0
	s_and_saveexec_b64 s[42:43], s[0:1]
	s_cbranch_execz .LBB0_401
	v_or3_b32 v13, v12, v10, 24
	v_mul_lo_u32 v24, v5, v13
	v_mad_u64_u32 v[22:23], s[2:3], v4, v13, 0
	v_add3_u32 v23, v23, v0, v24
	v_lshl_add_u64 v[22:23], v[22:23], 2, v[14:15]
	s_waitcnt vmcnt(0)
	v_mov_b32_e32 v22, v106
	s_and_saveexec_b64 s[52:53], vcc
	s_cbranch_execz .LBB0_400
	v_mov_b32_e32 v13, v1
	v_lshl_add_u64 v[24:25], v[12:13], 0, v[10:11]
	v_lshl_add_u64 v[24:25], v[24:25], 2, v[8:9]
	v_mov_b32_e32 v13, v122
	s_waitcnt vmcnt(0)
	v_mul_f32_e32 v22, v22, v13

; DI void wconv_tile(const float* __restrict__ src, int K, int Ns, const float* __restrict__ g, bf16_t* __restrict__ dst, int mode, int nt, int kt, char* lds) {
;     ...
;     for (int i = 0; i < 16; ++i) {
;       const int kl = (tid >> 6) + 4 * i, k = kt * 64 + kl;
;       float v = 0.f;
;       if (sc >= 0) { v = __builtin_nontemporal_load(src + (size_t)k * Ns + sc); if (g) v *= g[k]; }
;       tl[kl * 65 + nl] = v;
.LBB0_401:
	s_or_b64 exec, exec, s[42:43]
	v_add_u32_e32 v21, 0x410, v21
	v_add3_u32 v13, v250, v21, v16
	s_waitcnt vmcnt(0)
	ds_write_b32 v13, v22
	s_and_saveexec_b64 s[42:43], s[0:1]
	s_cbranch_execz .LBB0_405
	v_or3_b32 v13, v12, v10, 28
	v_mul_lo_u32 v17, v5, v13
	v_mad_u64_u32 v[22:23], s[2:3], v4, v13, 0
	v_add3_u32 v23, v23, v0, v17
	v_lshl_add_u64 v[22:23], v[22:23], 2, v[14:15]
	s_waitcnt vmcnt(0)
	v_mov_b32_e32 v17, v107
	s_and_saveexec_b64 s[52:53], vcc
	s_cbranch_execz .LBB0_404
	v_mov_b32_e32 v13, v1
	v_lshl_add_u64 v[22:23], v[12:13], 0, v[10:11]
	v_lshl_add_u64 v[22:23], v[22:23], 2, v[8:9]
	v_mov_b32_e32 v13, v123
	s_waitcnt vmcnt(0)
	v_mul_f32_e32 v17, v17, v13

; DI void wconv_tile(const float* __restrict__ src, int K, int Ns, const float* __restrict__ g, bf16_t* __restrict__ dst, int mode, int nt, int kt, char* lds) {
;     ...
;     for (int i = 0; i < 16; ++i) {
;       const int kl = (tid >> 6) + 4 * i, k = kt * 64 + kl;
;       float v = 0.f;
;       if (sc >= 0) { v = __builtin_nontemporal_load(src + (size_t)k * Ns + sc); if (g) v *= g[k]; }
;       tl[kl * 65 + nl] = v;
.LBB0_405:
	s_or_b64 exec, exec, s[42:43]
	v_add_u32_e32 v21, 0x410, v21
	v_add3_u32 v13, v250, v21, v16
	s_waitcnt vmcnt(0)
	ds_write_b32 v13, v17
	v_mov_b32_e32 v17, 0
	v_mov_b32_e32 v22, 0
	s_and_saveexec_b64 s[42:43], s[0:1]
	s_cbranch_execz .LBB0_409
	v_or3_b32 v13, v12, v10, 32
	v_mul_lo_u32 v24, v5, v13
	v_mad_u64_u32 v[22:23], s[2:3], v4, v13, 0
	v_add3_u32 v23, v23, v0, v24
	v_lshl_add_u64 v[22:23], v[22:23], 2, v[14:15]
	s_waitcnt vmcnt(0)
	v_mov_b32_e32 v22, v108
	s_and_saveexec_b64 s[52:53], vcc
	s_cbranch_execz .LBB0_408
	v_mov_b32_e32 v13, v1
	v_lshl_add_u64 v[24:25], v[12:13], 0, v[10:11]
	v_lshl_add_u64 v[24:25], v[24:25], 2, v[8:9]
	v_mov_b32_e32 v13, v124
	s_waitcnt vmcnt(0)
	v_mul_f32_e32 v22, v22, v13

; DI void wconv_tile(const float* __restrict__ src, int K, int Ns, const float* __restrict__ g, bf16_t* __restrict__ dst, int mode, int nt, int kt, char* lds) {
;     ...
;     for (int i = 0; i < 16; ++i) {
;       const int kl = (tid >> 6) + 4 * i, k = kt * 64 + kl;
;       float v = 0.f;
;       if (sc >= 0) { v = __builtin_nontemporal_load(src + (size_t)k * Ns + sc); if (g) v *= g[k]; }
;       tl[kl * 65 + nl] = v;
.LBB0_409:
	s_or_b64 exec, exec, s[42:43]
	v_add_u32_e32 v21, 0x410, v21
	v_add3_u32 v13, v250, v21, v16
	s_waitcnt vmcnt(0)
	ds_write_b32 v13, v22
	s_and_saveexec_b64 s[42:43], s[0:1]
	s_cbranch_execz .LBB0_413
	v_or3_b32 v13, v12, v10, 36
	v_mul_lo_u32 v17, v5, v13
	v_mad_u64_u32 v[22:23], s[2:3], v4, v13, 0
	v_add3_u32 v23, v23, v0, v17
	v_lshl_add_u64 v[22:23], v[22:23], 2, v[14:15]
	s_waitcnt vmcnt(0)
	v_mov_b32_e32 v17, v109
	s_and_saveexec_b64 s[52:53], vcc
	s_cbranch_execz .LBB0_412
	v_mov_b32_e32 v13, v1
	v_lshl_add_u64 v[22:23], v[12:13], 0, v[10:11]
	v_lshl_add_u64 v[22:23], v[22:23], 2, v[8:9]
	v_mov_b32_e32 v13, v125
	s_waitcnt vmcnt(0)
	v_mul_f32_e32 v17, v17, v13

; DI void wconv_tile(const float* __restrict__ src, int K, int Ns, const float* __restrict__ g, bf16_t* __restrict__ dst, int mode, int nt, int kt, char* lds) {
;     ...
;     for (int i = 0; i < 16; ++i) {
;       const int kl = (tid >> 6) + 4 * i, k = kt * 64 + kl;
;       float v = 0.f;
;       if (sc >= 0) { v = __builtin_nontemporal_load(src + (size_t)k * Ns + sc); if (g) v *= g[k]; }
;       tl[kl * 65 + nl] = v;
.LBB0_413:
	s_or_b64 exec, exec, s[42:43]
	v_add_u32_e32 v21, 0x410, v21
	v_add3_u32 v13, v250, v21, v16
	s_waitcnt vmcnt(0)
	ds_write_b32 v13, v17
	v_mov_b32_e32 v17, 0
	v_mov_b32_e32 v22, 0
	s_and_saveexec_b64 s[42:43], s[0:1]
	s_cbranch_execz .LBB0_417
	v_or3_b32 v13, v12, v10, 40
	v_mul_lo_u32 v24, v5, v13
	v_mad_u64_u32 v[22:23], s[2:3], v4, v13, 0
	v_add3_u32 v23, v23, v0, v24
	v_lshl_add_u64 v[22:23], v[22:23], 2, v[14:15]
	s_waitcnt vmcnt(0)
	v_mov_b32_e32 v22, v110
	s_and_saveexec_b64 s[52:53], vcc
	s_cbranch_execz .LBB0_416
	v_mov_b32_e32 v13, v1
	v_lshl_add_u64 v[24:25], v[12:13], 0, v[10:11]
	v_lshl_add_u64 v[24:25], v[24:25], 2, v[8:9]
	v_mov_b32_e32 v13, v126
	s_waitcnt vmcnt(0)
	v_mul_f32_e32 v22, v22, v13

; DI void wconv_tile(const float* __restrict__ src, int K, int Ns, const float* __restrict__ g, bf16_t* __restrict__ dst, int mode, int nt, int kt, char* lds) {
;     ...
;     for (int i = 0; i < 16; ++i) {
;       const int kl = (tid >> 6) + 4 * i, k = kt * 64 + kl;
;       float v = 0.f;
;       if (sc >= 0) { v = __builtin_nontemporal_load(src + (size_t)k * Ns + sc); if (g) v *= g[k]; }
;       tl[kl * 65 + nl] = v;
.LBB0_417:
	s_or_b64 exec, exec, s[42:43]
	v_add_u32_e32 v21, 0x410, v21
	v_add3_u32 v13, v250, v21, v16
	s_waitcnt vmcnt(0)
	ds_write_b32 v13, v22
	s_and_saveexec_b64 s[42:43], s[0:1]
	s_cbranch_execz .LBB0_421
	v_or3_b32 v13, v12, v10, 44
	v_mul_lo_u32 v17, v5, v13
	v_mad_u64_u32 v[22:23], s[2:3], v4, v13, 0
	v_add3_u32 v23, v23, v0, v17
	v_lshl_add_u64 v[22:23], v[22:23], 2, v[14:15]
	s_waitcnt vmcnt(0)
	v_mov_b32_e32 v17, v111
	s_and_saveexec_b64 s[52:53], vcc
	s_cbranch_execz .LBB0_420
	v_mov_b32_e32 v13, v1
	v_lshl_add_u64 v[22:23], v[12:13], 0, v[10:11]
	v_lshl_add_u64 v[22:23], v[22:23], 2, v[8:9]
	v_mov_b32_e32 v13, v127
	s_waitcnt vmcnt(0)
	v_mul_f32_e32 v17, v17, v13

; DI void wconv_tile(const float* __restrict__ src, int K, int Ns, const float* __restrict__ g, bf16_t* __restrict__ dst, int mode, int nt, int kt, char* lds) {
;     ...
;     for (int i = 0; i < 16; ++i) {
;       const int kl = (tid >> 6) + 4 * i, k = kt * 64 + kl;
;       float v = 0.f;
;       if (sc >= 0) { v = __builtin_nontemporal_load(src + (size_t)k * Ns + sc); if (g) v *= g[k]; }
;       tl[kl * 65 + nl] = v;
.LBB0_421:
	s_or_b64 exec, exec, s[42:43]
	v_add_u32_e32 v21, 0x410, v21
	v_add3_u32 v13, v250, v21, v16
	s_waitcnt vmcnt(0)
	ds_write_b32 v13, v17
	v_mov_b32_e32 v17, 0
	v_mov_b32_e32 v22, 0
	s_and_saveexec_b64 s[42:43], s[0:1]
	s_cbranch_execz .LBB0_425
	v_or3_b32 v13, v12, v10, 48
	v_mul_lo_u32 v24, v5, v13
	v_mad_u64_u32 v[22:23], s[2:3], v4, v13, 0
	v_add3_u32 v23, v23, v0, v24
	v_lshl_add_u64 v[22:23], v[22:23], 2, v[14:15]
	s_waitcnt vmcnt(0)
	v_mov_b32_e32 v22, v112
	s_and_saveexec_b64 s[52:53], vcc
	s_cbranch_execz .LBB0_424
	v_mov_b32_e32 v13, v1
	v_lshl_add_u64 v[24:25], v[12:13], 0, v[10:11]
	v_lshl_add_u64 v[24:25], v[24:25], 2, v[8:9]
	v_mov_b32_e32 v13, v128
	s_waitcnt vmcnt(0)
	v_mul_f32_e32 v22, v22, v13

; DI void wconv_tile(const float* __restrict__ src, int K, int Ns, const float* __restrict__ g, bf16_t* __restrict__ dst, int mode, int nt, int kt, char* lds) {
;     ...
;     for (int i = 0; i < 16; ++i) {
;       const int kl = (tid >> 6) + 4 * i, k = kt * 64 + kl;
;       float v = 0.f;
;       if (sc >= 0) { v = __builtin_nontemporal_load(src + (size_t)k * Ns + sc); if (g) v *= g[k]; }
;       tl[kl * 65 + nl] = v;
.LBB0_425:
	s_or_b64 exec, exec, s[42:43]
	v_add_u32_e32 v21, 0x410, v21
	v_add3_u32 v13, v250, v21, v16
	s_waitcnt vmcnt(0)
	ds_write_b32 v13, v22
	s_and_saveexec_b64 s[42:43], s[0:1]
	s_cbranch_execz .LBB0_429
	v_or3_b32 v13, v12, v10, 52
	v_mul_lo_u32 v17, v5, v13
	v_mad_u64_u32 v[22:23], s[2:3], v4, v13, 0
	v_add3_u32 v23, v23, v0, v17
	v_lshl_add_u64 v[22:23], v[22:23], 2, v[14:15]
	s_waitcnt vmcnt(0)
	v_mov_b32_e32 v17, v113
	s_and_saveexec_b64 s[52:53], vcc
	s_cbranch_execz .LBB0_428
	v_mov_b32_e32 v13, v1
	v_lshl_add_u64 v[22:23], v[12:13], 0, v[10:11]
	v_lshl_add_u64 v[22:23], v[22:23], 2, v[8:9]
	v_mov_b32_e32 v13, v129
	s_waitcnt vmcnt(0)
	v_mul_f32_e32 v17, v17, v13

; DI void wconv_tile(const float* __restrict__ src, int K, int Ns, const float* __restrict__ g, bf16_t* __restrict__ dst, int mode, int nt, int kt, char* lds) {
;     ...
;     for (int i = 0; i < 16; ++i) {
;       const int kl = (tid >> 6) + 4 * i, k = kt * 64 + kl;
;       float v = 0.f;
;       if (sc >= 0) { v = __builtin_nontemporal_load(src + (size_t)k * Ns + sc); if (g) v *= g[k]; }
;       tl[kl * 65 + nl] = v;
.LBB0_429:
	s_or_b64 exec, exec, s[42:43]
	v_add_u32_e32 v21, 0x410, v21
	v_add3_u32 v13, v250, v21, v16
	s_waitcnt vmcnt(0)
	ds_write_b32 v13, v17
	v_mov_b32_e32 v17, 0
	v_mov_b32_e32 v22, 0
	s_and_saveexec_b64 s[42:43], s[0:1]
	s_cbranch_execz .LBB0_433
	v_or3_b32 v13, v12, v10, 56
	v_mul_lo_u32 v24, v5, v13
	v_mad_u64_u32 v[22:23], s[2:3], v4, v13, 0
	v_add3_u32 v23, v23, v0, v24
	v_lshl_add_u64 v[22:23], v[22:23], 2, v[14:15]
	s_waitcnt vmcnt(0)
	v_mov_b32_e32 v22, v114
	s_and_saveexec_b64 s[52:53], vcc
	s_cbranch_execz .LBB0_432
	v_mov_b32_e32 v13, v1
	v_lshl_add_u64 v[24:25], v[12:13], 0, v[10:11]
	v_lshl_add_u64 v[24:25], v[24:25], 2, v[8:9]
	v_mov_b32_e32 v13, v130
	s_waitcnt vmcnt(0)
	v_mul_f32_e32 v22, v22, v13

; DI void wconv_tile(const float* __restrict__ src, int K, int Ns, const float* __restrict__ g, bf16_t* __restrict__ dst, int mode, int nt, int kt, char* lds) {
;     ...
;     for (int i = 0; i < 16; ++i) {
;       const int kl = (tid >> 6) + 4 * i, k = kt * 64 + kl;
;       float v = 0.f;
;       if (sc >= 0) { v = __builtin_nontemporal_load(src + (size_t)k * Ns + sc); if (g) v *= g[k]; }
;       tl[kl * 65 + nl] = v;
.LBB0_433:
	s_or_b64 exec, exec, s[42:43]
	v_add_u32_e32 v13, 0x410, v21
	v_add3_u32 v16, v250, v13, v16
	s_waitcnt vmcnt(0)
	ds_write_b32 v16, v22
	s_and_saveexec_b64 s[42:43], s[0:1]
	s_cbranch_execz .LBB0_330
	v_or3_b32 v13, v12, v10, 60
	v_mul_lo_u32 v17, v5, v13
	v_mad_u64_u32 v[4:5], s[0:1], v4, v13, 0
	v_add3_u32 v5, v5, v0, v17
	v_lshl_add_u64 v[4:5], v[4:5], 2, v[14:15]
	s_waitcnt vmcnt(0)
	v_mov_b32_e32 v17, v115
	s_and_saveexec_b64 s[0:1], vcc
	s_cbranch_execz .LBB0_329
	v_mov_b32_e32 v13, v1
	v_lshl_add_u64 v[4:5], v[12:13], 0, v[10:11]
	v_lshl_add_u64 v[4:5], v[4:5], 2, v[8:9]
	v_mov_b32_e32 v0, v131
	s_waitcnt vmcnt(0)
	v_mul_f32_e32 v17, v17, v0
	s_branch .LBB0_329
